# weight-transpose loops with runtime gain check: 8 weight + 8 gain loads issued back-to-back per 16-row step instead of load-wait-mul serial chain
# speedup vs baseline: 1.0027x; 1.0027x over previous
; __device__ __forceinline__ void transpose_item(const float* W, int K, int N, bf16_t* WT, const float* gain, int mode, LAS float* scr, int item, int lane) {
;     ...
; #pragma unroll 8
;     for (int i = 0; i < 32; ++i) { const int kk = 2 * i + (lane >> 5); float w = __builtin_nontemporal_load(W + (size_t)(k0 + kk) * N + n0 + (lane & 31)); if (gain) w *= gain[k0 + kk]; scr[kk * 33 + (lane & 31)] = w; }
.LBB0_326:
	s_add_u32 s10, s10, 0x58000
	s_addc_u32 s11, s11, 0
	v_add_u32_e32 v20, 0x840, v20
	s_cmp_lg_u32 s10, 0x160000
	v_lshl_add_u64 v[10:11], v[10:11], 0, 64
	s_cbranch_scc0 .LBB0_343
.LBB0_327:
	v_lshl_add_u64 v[116:117], v[6:7], 0, s[10:11]
	global_load_dword v100, v[116:117], off nt
	v_lshl_add_u64 v[118:119], v[18:19], 0, s[10:11]
	global_load_dword v101, v[118:119], off nt
	v_lshl_add_u64 v[120:121], v[16:17], 0, s[10:11]
	global_load_dword v102, v[120:121], off nt
	v_lshl_add_u64 v[122:123], v[14:15], 0, s[10:11]
	global_load_dword v103, v[122:123], off nt
	v_lshl_add_u64 v[124:125], v[12:13], 0, s[10:11]
	global_load_dword v104, v[124:125], off nt
	v_lshl_add_u64 v[126:127], v[8:9], 0, s[10:11]
	global_load_dword v105, v[126:127], off nt
	v_lshl_add_u64 v[128:129], v[4:5], 0, s[10:11]
	global_load_dword v106, v[128:129], off nt
	v_lshl_add_u64 v[130:131], v[2:3], 0, s[10:11]
	global_load_dword v107, v[130:131], off nt
	v_cndmask_b32_e64 v22, 0, 1, s[16:17]
	v_cmp_ne_u32_e64 s[40:41], 1, v22
	s_andn2_b64 vcc, exec, s[16:17]
	s_cbranch_vccnz .LBB0_329
	global_load_dword v108, v[10:11], off offset:-56
	global_load_dword v109, v[10:11], off offset:-48
	global_load_dword v110, v[10:11], off offset:-40
	global_load_dword v111, v[10:11], off offset:-32
	global_load_dword v112, v[10:11], off offset:-24
	global_load_dword v113, v[10:11], off offset:-16
	global_load_dword v114, v[10:11], off offset:-8
	global_load_dword v115, v[10:11], off
	s_waitcnt vmcnt(0)
	v_mul_f32_e32 v100, v100, v108
	v_mul_f32_e32 v101, v101, v109
	v_mul_f32_e32 v102, v102, v110
	v_mul_f32_e32 v103, v103, v111
	v_mul_f32_e32 v104, v104, v112
	v_mul_f32_e32 v105, v105, v113
	v_mul_f32_e32 v106, v106, v114
	v_mul_f32_e32 v107, v107, v115
.LBB0_329:
	s_waitcnt vmcnt(0)
	ds_write_b32 v20, v100
	ds_write_b32 v20, v101 offset:264
	ds_write_b32 v20, v102 offset:528
	ds_write_b32 v20, v103 offset:792
	ds_write_b32 v20, v104 offset:1056
	ds_write_b32 v20, v105 offset:1320
	ds_write_b32 v20, v106 offset:1584
	ds_write_b32 v20, v107 offset:1848
	s_branch .LBB0_326

; __device__ __forceinline__ void transpose_item(const float* W, int K, int N, bf16_t* WT, const float* gain, int mode, LAS float* scr, int item, int lane) {
;     ...
; #pragma unroll 8
;     for (int i = 0; i < 32; ++i) { const int kk = 2 * i + (lane >> 5); float w = __builtin_nontemporal_load(W + (size_t)(k0 + kk) * N + n0 + (lane & 31)); if (gain) w *= gain[k0 + kk]; scr[kk * 33 + (lane & 31)] = w; }
.LBB0_362:
	s_add_i32 s2, s2, 16
	s_mov_b64 s[38:39], 0x24000
	v_add_u32_e32 v9, 0x840, v9
	v_lshl_add_u64 v[4:5], v[4:5], 0, s[38:39]
	s_cmp_lg_u32 s2, 64
	v_lshl_add_u64 v[6:7], v[6:7], 0, 64
	s_cbranch_scc0 .LBB0_302
.LBB0_363:
	global_load_dword v100, v[4:5], off nt
	v_cndmask_b32_e64 v0, 0, 1, s[18:19]
	v_cmp_ne_u32_e64 s[40:41], 1, v0
	v_add_u32_e32 v0, s2, v10
	v_add_u32_e32 v12, 2, v0
	v_mad_i64_i32 v[118:119], s[38:39], v12, s91, v[2:3]
	global_load_dword v101, v[118:119], off nt
	v_add_u32_e32 v12, 4, v0
	v_mad_i64_i32 v[120:121], s[38:39], v12, s91, v[2:3]
	global_load_dword v102, v[120:121], off nt
	v_add_u32_e32 v12, 6, v0
	v_mad_i64_i32 v[122:123], s[38:39], v12, s91, v[2:3]
	global_load_dword v103, v[122:123], off nt
	v_add_u32_e32 v12, 8, v0
	v_mad_i64_i32 v[124:125], s[38:39], v12, s91, v[2:3]
	global_load_dword v104, v[124:125], off nt
	v_add_u32_e32 v12, 10, v0
	v_mad_i64_i32 v[126:127], s[38:39], v12, s91, v[2:3]
	global_load_dword v105, v[126:127], off nt
	v_add_u32_e32 v12, 12, v0
	v_mad_i64_i32 v[128:129], s[38:39], v12, s91, v[2:3]
	global_load_dword v106, v[128:129], off nt
	v_add_u32_e32 v12, 14, v0
	v_mad_i64_i32 v[130:131], s[38:39], v12, s91, v[2:3]
	global_load_dword v107, v[130:131], off nt
	s_andn2_b64 vcc, exec, s[18:19]
	s_cbranch_vccnz .LBB0_365
	global_load_dword v108, v[6:7], off offset:-56
	global_load_dword v109, v[6:7], off offset:-48
	global_load_dword v110, v[6:7], off offset:-40
	global_load_dword v111, v[6:7], off offset:-32
	global_load_dword v112, v[6:7], off offset:-24
	global_load_dword v113, v[6:7], off offset:-16
	global_load_dword v114, v[6:7], off offset:-8
	global_load_dword v115, v[6:7], off
	s_waitcnt vmcnt(0)
	v_mul_f32_e32 v100, v100, v108
	v_mul_f32_e32 v101, v101, v109
	v_mul_f32_e32 v102, v102, v110
	v_mul_f32_e32 v103, v103, v111
	v_mul_f32_e32 v104, v104, v112
	v_mul_f32_e32 v105, v105, v113
	v_mul_f32_e32 v106, v106, v114
	v_mul_f32_e32 v107, v107, v115
.LBB0_365:
	s_waitcnt vmcnt(0)
	ds_write_b32 v9, v100
	ds_write_b32 v9, v101 offset:264
	ds_write_b32 v9, v102 offset:528
	ds_write_b32 v9, v103 offset:792
	ds_write_b32 v9, v104 offset:1056
	ds_write_b32 v9, v105 offset:1320
	ds_write_b32 v9, v106 offset:1584
	ds_write_b32 v9, v107 offset:1848
	s_branch .LBB0_362
